# k9 + attention M blocks thinned: hipcc s_nop pads before MFMA removed, one counted lgkmcnt wait per MFMA pair (issue-bound loop)
# speedup vs baseline: 1.0047x; 1.0046x over previous
.LBB0_526:
	s_add_i32 s8, s97, s96
	s_add_i32 s7, s8, -2
	s_cmp_lt_i32 s7, 0
	s_cselect_b64 s[4:5], -1, 0
	s_cmp_le_i32 s95, s68
	s_cselect_b64 s[12:13], -1, 0
	s_or_b64 s[12:13], s[4:5], s[12:13]
	v_cndmask_b32_e64 v0, 0, 1, s[12:13]
	v_cmp_ne_u32_e64 s[4:5], 1, v0
	s_andn2_b64 vcc, exec, s[12:13]
	s_mov_b32 s72, s10
	s_cbranch_vccnz .LBB0_528
	s_mul_i32 s9, s72, 0x6000
	v_add_u32_e32 v0, s9, v193
	ds_read_b128 v[2:5], v0 offset:0
	ds_read_b128 v[6:9], v0 offset:0x2000
	v_add_u32_e32 v14, s9, v195
	ds_read_b128 v[10:13], v14 offset:0
	ds_read_b128 v[210:213], v14 offset:0x2000
	v_add_u32_e32 v15, s9, v197
	ds_read_b128 v[214:217], v15 offset:0
	v_add_u32_e32 v209, s9, v199
	s_waitcnt lgkmcnt(3)
	v_mfma_f32_32x32x16_bf16 v[80:95], v[2:5], v[112:115], 0
	ds_read_b128 v[2:5], v15 offset:0x2000
	v_mfma_f32_32x32x16_bf16 v[96:111], v[6:9], v[112:115], 0
	ds_read_b128 v[6:9], v209 offset:0
	s_waitcnt lgkmcnt(3)
	v_mfma_f32_32x32x16_bf16 v[80:95], v[10:13], v[116:119], v[80:95]
	ds_read_b128 v[10:13], v209 offset:0x2000
	v_mfma_f32_32x32x16_bf16 v[96:111], v[210:213], v[116:119], v[96:111]
	ds_read_b128 v[210:213], v0 offset:0x80
	s_waitcnt lgkmcnt(3)
	v_mfma_f32_32x32x16_bf16 v[80:95], v[214:217], v[120:123], v[80:95]
	ds_read_b128 v[214:217], v0 offset:0x2080
	v_add_u32_e32 v0, s9, v194
	v_mfma_f32_32x32x16_bf16 v[96:111], v[2:5], v[120:123], v[96:111]
	ds_read_b128 v[2:5], v14 offset:0x80
	s_waitcnt lgkmcnt(3)
	v_mfma_f32_32x32x16_bf16 v[80:95], v[6:9], v[124:127], v[80:95]
	ds_read_b128 v[6:9], v14 offset:0x2080
	v_mfma_f32_32x32x16_bf16 v[96:111], v[10:13], v[124:127], v[96:111]
	ds_read_b128 v[10:13], v15 offset:0x80
	s_waitcnt lgkmcnt(3)
	v_mfma_f32_32x32x16_bf16 v[80:95], v[210:213], v[128:131], v[80:95]
	ds_read_b128 v[210:213], v15 offset:0x2080
	v_mfma_f32_32x32x16_bf16 v[96:111], v[214:217], v[128:131], v[96:111]
	ds_read_b128 v[214:217], v209 offset:0x80
	s_waitcnt lgkmcnt(3)
	v_mfma_f32_32x32x16_bf16 v[80:95], v[2:5], v[132:135], v[80:95]
	ds_read_b128 v[2:5], v209 offset:0x2080
	v_mfma_f32_32x32x16_bf16 v[96:111], v[6:9], v[132:135], v[96:111]
	ds_read_b128 v[6:9], v0 offset:0
	ds_read_b128 v[218:221], v169 offset:0
	s_waitcnt lgkmcnt(4)
	v_mfma_f32_32x32x16_bf16 v[80:95], v[10:13], v[136:139], v[80:95]
	ds_read_b128 v[10:13], v0 offset:0x1000
	v_add_u32_e32 v0, s9, v196
	v_mfma_f32_32x32x16_bf16 v[96:111], v[210:213], v[136:139], v[96:111]
	ds_read_b128 v[210:213], v0 offset:0
	ds_read_b128 v[222:225], v169 offset:0x400
	s_waitcnt lgkmcnt(5)
	v_mfma_f32_32x32x16_bf16 v[80:95], v[214:217], v[140:143], v[80:95]
	ds_read_b128 v[214:217], v0 offset:0x1000
	v_add_u32_e32 v0, s9, v198
	v_mfma_f32_32x32x16_bf16 v[96:111], v[2:5], v[140:143], v[96:111]
	ds_read_b128 v[2:5], v0 offset:0
	ds_read_b128 v[226:229], v169 offset:0x800
	s_waitcnt lgkmcnt(5)
	v_mfma_f32_32x32x16_bf16 v[80:95], v[6:9], v[218:221], v[80:95]
	ds_read_b128 v[6:9], v0 offset:0x1000
	v_add_u32_e32 v0, s9, v200
	v_mfma_f32_32x32x16_bf16 v[96:111], v[10:13], v[218:221], v[96:111]
	ds_read_b128 v[10:13], v0 offset:0
	ds_read_b128 v[218:221], v169 offset:0xc00
	s_waitcnt lgkmcnt(5)
	v_mfma_f32_32x32x16_bf16 v[80:95], v[210:213], v[222:225], v[80:95]
	ds_read_b128 v[210:213], v0 offset:0x1000
	v_mfma_f32_32x32x16_bf16 v[96:111], v[214:217], v[222:225], v[96:111]
	s_waitcnt lgkmcnt(3)
	v_mfma_f32_32x32x16_bf16 v[80:95], v[2:5], v[226:229], v[80:95]
	v_mfma_f32_32x32x16_bf16 v[96:111], v[6:9], v[226:229], v[96:111]
	s_waitcnt lgkmcnt(0)
	v_mfma_f32_32x32x16_bf16 v[80:95], v[10:13], v[218:221], v[80:95]
	v_mfma_f32_32x32x16_bf16 v[96:111], v[210:213], v[218:221], v[96:111]
.LBB0_528:
	s_cmp_eq_u32 s96, 2
	s_cbranch_scc1 .LBB0_531
	s_add_i32 s8, s8, -3
	s_cmp_gt_i32 s8, -1
	s_cselect_b64 s[8:9], -1, 0
	s_sub_i32 s10, s95, 64
	s_cmp_gt_i32 s10, s68
	s_cselect_b64 s[10:11], -1, 0
	s_and_b64 s[8:9], s[8:9], s[10:11]
	s_and_b64 vcc, exec, s[8:9]
	s_cbranch_vccnz .LBB0_531
	v_lshl_add_u32 v0, s6, 14, v202
	ds_read_b64_tr_b16 v[2:3], v0 offset:0
	ds_read_b64_tr_b16 v[4:5], v0 offset:0x800
	ds_read_b64_tr_b16 v[6:7], v0 offset:0x1000
	ds_read_b64_tr_b16 v[8:9], v0 offset:0x1800
	ds_read_b64_tr_b16 v[10:11], v0 offset:0x2000
	ds_read_b64_tr_b16 v[12:13], v0 offset:0x2800
	ds_read_b64_tr_b16 v[210:211], v0 offset:0x3000
	ds_read_b64_tr_b16 v[212:213], v0 offset:0x3800
	s_waitcnt lgkmcnt(4)
	v_mfma_f32_32x32x16_bf16 v[64:79], v[2:5], v[156:159], v[64:79]
	ds_read_b64_tr_b16 v[2:3], v0 offset:0x200
	ds_read_b64_tr_b16 v[4:5], v0 offset:0xa00
	v_mfma_f32_32x32x16_bf16 v[64:79], v[6:9], v[152:155], v[64:79]
	ds_read_b64_tr_b16 v[6:7], v0 offset:0x1200
	ds_read_b64_tr_b16 v[8:9], v0 offset:0x1a00
	s_waitcnt lgkmcnt(4)
	v_mfma_f32_32x32x16_bf16 v[64:79], v[10:13], v[148:151], v[64:79]
	ds_read_b64_tr_b16 v[10:11], v0 offset:0x2200
	ds_read_b64_tr_b16 v[12:13], v0 offset:0x2a00
	v_mfma_f32_32x32x16_bf16 v[64:79], v[210:213], v[144:147], v[64:79]
	ds_read_b64_tr_b16 v[210:211], v0 offset:0x3200
	ds_read_b64_tr_b16 v[212:213], v0 offset:0x3a00
	s_waitcnt lgkmcnt(4)
	v_mfma_f32_32x32x16_bf16 v[48:63], v[2:5], v[156:159], v[48:63]
	ds_read_b64_tr_b16 v[2:3], v0 offset:0x400
	ds_read_b64_tr_b16 v[4:5], v0 offset:0xc00
	v_mfma_f32_32x32x16_bf16 v[48:63], v[6:9], v[152:155], v[48:63]
	ds_read_b64_tr_b16 v[6:7], v0 offset:0x1400
	ds_read_b64_tr_b16 v[8:9], v0 offset:0x1c00
	s_waitcnt lgkmcnt(4)
	v_mfma_f32_32x32x16_bf16 v[48:63], v[10:13], v[148:151], v[48:63]
	ds_read_b64_tr_b16 v[10:11], v0 offset:0x2400
	ds_read_b64_tr_b16 v[12:13], v0 offset:0x2c00
	v_mfma_f32_32x32x16_bf16 v[48:63], v[210:213], v[144:147], v[48:63]
	ds_read_b64_tr_b16 v[210:211], v0 offset:0x3400
	ds_read_b64_tr_b16 v[212:213], v0 offset:0x3c00
	s_waitcnt lgkmcnt(4)
	v_mfma_f32_32x32x16_bf16 v[32:47], v[2:5], v[156:159], v[32:47]
	ds_read_b64_tr_b16 v[2:3], v0 offset:0x600
	ds_read_b64_tr_b16 v[4:5], v0 offset:0xe00
	v_mfma_f32_32x32x16_bf16 v[32:47], v[6:9], v[152:155], v[32:47]
	ds_read_b64_tr_b16 v[6:7], v0 offset:0x1600
	ds_read_b64_tr_b16 v[8:9], v0 offset:0x1e00
	s_waitcnt lgkmcnt(4)
	v_mfma_f32_32x32x16_bf16 v[32:47], v[10:13], v[148:151], v[32:47]
	ds_read_b64_tr_b16 v[10:11], v0 offset:0x2600
	ds_read_b64_tr_b16 v[12:13], v0 offset:0x2e00
	v_mfma_f32_32x32x16_bf16 v[32:47], v[210:213], v[144:147], v[32:47]
	ds_read_b64_tr_b16 v[210:211], v0 offset:0x3600
	ds_read_b64_tr_b16 v[212:213], v0 offset:0x3e00
	s_waitcnt lgkmcnt(4)
	v_mfma_f32_32x32x16_bf16 v[16:31], v[2:5], v[156:159], v[16:31]
	v_mfma_f32_32x32x16_bf16 v[16:31], v[6:9], v[152:155], v[16:31]
	s_waitcnt lgkmcnt(0)
	v_mfma_f32_32x32x16_bf16 v[16:31], v[10:13], v[148:151], v[16:31]
	v_mfma_f32_32x32x16_bf16 v[16:31], v[210:213], v[144:147], v[16:31]

.LBB0_573:
	s_add_i32 s7, s69, s0
	s_cmp_lt_i32 s7, 0
	s_cselect_b64 s[4:5], -1, 0
	s_add_i32 s8, s68, s86
	s_add_i32 s9, s8, 0xffffff80
	s_cmp_le_i32 s9, s95
	s_cselect_b64 s[10:11], -1, 0
	s_or_b64 s[10:11], s[4:5], s[10:11]
	v_cndmask_b32_e64 v2, 0, 1, s[10:11]
	v_cmp_ne_u32_e64 s[4:5], 1, v2
	s_andn2_b64 vcc, exec, s[10:11]
	s_cbranch_vccnz .LBB0_575
	s_mul_i32 s9, s1, 0x6000
	v_add_u32_e32 v14, s9, v193
	ds_read_b128 v[2:5], v14 offset:0
	ds_read_b128 v[6:9], v14 offset:0x2000
	v_add_u32_e32 v15, s9, v195
	ds_read_b128 v[10:13], v15 offset:0
	ds_read_b128 v[174:177], v15 offset:0x2000
	v_add_u32_e32 v159, s9, v197
	ds_read_b128 v[178:181], v159 offset:0
	v_add_u32_e32 v163, s9, v199
	s_waitcnt lgkmcnt(3)
	v_mfma_f32_32x32x16_bf16 v[96:111], v[2:5], v[112:115], 0
	ds_read_b128 v[2:5], v159 offset:0x2000
	v_mfma_f32_32x32x16_bf16 v[80:95], v[6:9], v[112:115], 0
	ds_read_b128 v[6:9], v163 offset:0
	s_waitcnt lgkmcnt(3)
	v_mfma_f32_32x32x16_bf16 v[96:111], v[10:13], v[116:119], v[96:111]
	ds_read_b128 v[10:13], v163 offset:0x2000
	v_mfma_f32_32x32x16_bf16 v[80:95], v[174:177], v[116:119], v[80:95]
	ds_read_b128 v[174:177], v14 offset:0x80
	ds_read_b128 v[208:211], v156 offset:0
	s_waitcnt lgkmcnt(4)
	v_mfma_f32_32x32x16_bf16 v[96:111], v[178:181], v[120:123], v[96:111]
	ds_read_b128 v[178:181], v14 offset:0x2080
	v_mfma_f32_32x32x16_bf16 v[80:95], v[2:5], v[120:123], v[80:95]
	ds_read_b128 v[2:5], v15 offset:0x80
	ds_read_b128 v[212:215], v156 offset:0x400
	s_waitcnt lgkmcnt(5)
	v_mfma_f32_32x32x16_bf16 v[96:111], v[6:9], v[124:127], v[96:111]
	ds_read_b128 v[6:9], v15 offset:0x2080
	v_mfma_f32_32x32x16_bf16 v[80:95], v[10:13], v[124:127], v[80:95]
	ds_read_b128 v[10:13], v159 offset:0x80
	ds_read_b128 v[216:219], v156 offset:0x800
	s_waitcnt lgkmcnt(5)
	v_mfma_f32_32x32x16_bf16 v[96:111], v[174:177], v[208:211], v[96:111]
	ds_read_b128 v[174:177], v159 offset:0x2080
	v_mfma_f32_32x32x16_bf16 v[80:95], v[178:181], v[208:211], v[80:95]
	ds_read_b128 v[178:181], v163 offset:0x80
	ds_read_b128 v[208:211], v156 offset:0xc00
	s_waitcnt lgkmcnt(5)
	v_mfma_f32_32x32x16_bf16 v[96:111], v[2:5], v[212:215], v[96:111]
	ds_read_b128 v[2:5], v163 offset:0x2080
	v_mfma_f32_32x32x16_bf16 v[80:95], v[6:9], v[212:215], v[80:95]
	s_waitcnt lgkmcnt(3)
	v_mfma_f32_32x32x16_bf16 v[96:111], v[10:13], v[216:219], v[96:111]
	v_mfma_f32_32x32x16_bf16 v[80:95], v[174:177], v[216:219], v[80:95]
	s_waitcnt lgkmcnt(0)
	v_mfma_f32_32x32x16_bf16 v[96:111], v[178:181], v[208:211], v[96:111]
	v_mfma_f32_32x32x16_bf16 v[80:95], v[2:5], v[208:211], v[80:95]
.LBB0_575:
	s_cmp_eq_u32 s0, 0
	s_cbranch_scc1 .LBB0_578
	s_add_i32 s9, s7, -1
	s_cmp_gt_i32 s9, -1
	s_cselect_b64 s[10:11], -1, 0
	s_add_i32 s9, s8, 0xffffff40
	s_cmp_gt_i32 s9, s95
	s_cselect_b64 s[12:13], -1, 0
	s_and_b64 s[10:11], s[10:11], s[12:13]
	s_and_b64 vcc, exec, s[10:11]
	s_cbranch_vccnz .LBB0_578
	v_lshl_add_u32 v14, s6, 14, v202
	ds_read_b64_tr_b16 v[2:3], v14 offset:0
	ds_read_b64_tr_b16 v[4:5], v14 offset:0x800
	ds_read_b64_tr_b16 v[6:7], v14 offset:0x1000
	ds_read_b64_tr_b16 v[8:9], v14 offset:0x1800
	ds_read_b64_tr_b16 v[10:11], v14 offset:0x2000
	ds_read_b64_tr_b16 v[12:13], v14 offset:0x2800
	ds_read_b64_tr_b16 v[174:175], v14 offset:0x3000
	ds_read_b64_tr_b16 v[176:177], v14 offset:0x3800
	s_waitcnt lgkmcnt(4)
	v_mfma_f32_32x32x16_bf16 v[64:79], v[2:5], v[140:143], v[64:79]
	ds_read_b64_tr_b16 v[2:3], v14 offset:0x200
	ds_read_b64_tr_b16 v[4:5], v14 offset:0xa00
	v_mfma_f32_32x32x16_bf16 v[64:79], v[6:9], v[136:139], v[64:79]
	ds_read_b64_tr_b16 v[6:7], v14 offset:0x1200
	ds_read_b64_tr_b16 v[8:9], v14 offset:0x1a00
	s_waitcnt lgkmcnt(4)
	v_mfma_f32_32x32x16_bf16 v[64:79], v[10:13], v[132:135], v[64:79]
	ds_read_b64_tr_b16 v[10:11], v14 offset:0x2200
	ds_read_b64_tr_b16 v[12:13], v14 offset:0x2a00
	v_mfma_f32_32x32x16_bf16 v[64:79], v[174:177], v[128:131], v[64:79]
	ds_read_b64_tr_b16 v[174:175], v14 offset:0x3200
	ds_read_b64_tr_b16 v[176:177], v14 offset:0x3a00
	s_waitcnt lgkmcnt(4)
	v_mfma_f32_32x32x16_bf16 v[48:63], v[2:5], v[140:143], v[48:63]
	ds_read_b64_tr_b16 v[2:3], v14 offset:0x400
	ds_read_b64_tr_b16 v[4:5], v14 offset:0xc00
	v_mfma_f32_32x32x16_bf16 v[48:63], v[6:9], v[136:139], v[48:63]
	ds_read_b64_tr_b16 v[6:7], v14 offset:0x1400
	ds_read_b64_tr_b16 v[8:9], v14 offset:0x1c00
	s_waitcnt lgkmcnt(4)
	v_mfma_f32_32x32x16_bf16 v[48:63], v[10:13], v[132:135], v[48:63]
	ds_read_b64_tr_b16 v[10:11], v14 offset:0x2400
	ds_read_b64_tr_b16 v[12:13], v14 offset:0x2c00
	v_mfma_f32_32x32x16_bf16 v[48:63], v[174:177], v[128:131], v[48:63]
	ds_read_b64_tr_b16 v[174:175], v14 offset:0x3400
	ds_read_b64_tr_b16 v[176:177], v14 offset:0x3c00
	s_waitcnt lgkmcnt(4)
	v_mfma_f32_32x32x16_bf16 v[32:47], v[2:5], v[140:143], v[32:47]
	ds_read_b64_tr_b16 v[2:3], v14 offset:0x600
	ds_read_b64_tr_b16 v[4:5], v14 offset:0xe00
	v_mfma_f32_32x32x16_bf16 v[32:47], v[6:9], v[136:139], v[32:47]
	ds_read_b64_tr_b16 v[6:7], v14 offset:0x1600
	ds_read_b64_tr_b16 v[8:9], v14 offset:0x1e00
	s_waitcnt lgkmcnt(4)
	v_mfma_f32_32x32x16_bf16 v[32:47], v[10:13], v[132:135], v[32:47]
	ds_read_b64_tr_b16 v[10:11], v14 offset:0x2600
	ds_read_b64_tr_b16 v[12:13], v14 offset:0x2e00
	v_mfma_f32_32x32x16_bf16 v[32:47], v[174:177], v[128:131], v[32:47]
	ds_read_b64_tr_b16 v[174:175], v14 offset:0x3600
	ds_read_b64_tr_b16 v[176:177], v14 offset:0x3e00
	s_waitcnt lgkmcnt(4)
	v_mfma_f32_32x32x16_bf16 v[16:31], v[2:5], v[140:143], v[16:31]
	v_mfma_f32_32x32x16_bf16 v[16:31], v[6:9], v[136:139], v[16:31]
	s_waitcnt lgkmcnt(0)
	v_mfma_f32_32x32x16_bf16 v[16:31], v[10:13], v[132:135], v[16:31]
	v_mfma_f32_32x32x16_bf16 v[16:31], v[174:177], v[128:131], v[16:31]
